# grid barrier tail by hand: last top-level arriver releases all per-XCD generation words directly, every workgroup polls only its own XCD word
# speedup vs baseline: 1.0062x; 1.0062x over previous
; __device__ __forceinline__ unsigned xb_ld(unsigned* p)              { return __hip_atomic_load(p, __ATOMIC_RELAXED, __HIP_MEMORY_SCOPE_AGENT); }
; __device__ __forceinline__ unsigned xb_add(unsigned* p, unsigned v) { return __hip_atomic_fetch_add(p, v, __ATOMIC_RELAXED, __HIP_MEMORY_SCOPE_AGENT); }
; #define XB_SPIN(cond, bar) do { unsigned _sp = 0; while (cond) { __builtin_amdgcn_s_sleep(1); \
;     if ((++_sp & 255u) == 0u) { if (xb_ld(&(bar)[XB_TMO])) break; if (_sp > XB_SPIN_CAP) { atomicAdd(&(bar)[XB_TMO], 1u); break; } } } } while (0)
; __device__ __forceinline__ void xcd_barrier(const XcdBarrier& b) {
;     ...
;     if (threadIdx.x == 0) {
;         unsigned* bar = b.bar;
;         __builtin_amdgcn_s_waitcnt(0);
;         unsigned nloc = b.st[0], nx = b.st[1];
;         if (nloc == 0u) { xcd_barrier_complete(bar, b.x, nloc, nx); b.st[0] = nloc; b.st[1] = nx; }
;         const unsigned old = xb_add(&bar[XB_XSUB(b.x)], 1u);
;         const unsigned gen = old / nloc;
;         if (old + 1u == (gen + 1u) * nloc) {
;             __builtin_amdgcn_fence(__ATOMIC_RELEASE, "agent");
;             asm volatile("s_waitcnt vmcnt(0)" ::: "memory");
;             const unsigned og = xb_add(&bar[XB_TOP], 1u);
;             const unsigned tg = og / nx;
;             if (og + 1u == (tg + 1u) * nx) xb_add(&bar[XB_TOPGEN], 1u);
;             else XB_SPIN(xb_ld(&bar[XB_TOPGEN]) == tg, bar);
;             __builtin_amdgcn_fence(__ATOMIC_ACQUIRE, "agent");
;             xb_add(&bar[XB_XGEN(b.x)], 1u);
;             asm volatile("s_waitcnt vmcnt(0)" ::: "memory");
;         } else {
;             XB_SPIN(xb_ld(&bar[XB_XGEN(b.x)]) == gen, bar);
;             __builtin_amdgcn_fence(__ATOMIC_ACQUIRE, "agent");
;             asm volatile("s_waitcnt vmcnt(0)" ::: "memory");
;         }
.LBB0_100:
	s_mov_b32 s2, 0x27ff0
	s_mov_b32 s3, 0x27ff4
	v_readlane_b32 s12, v254, 41
	v_readlane_b32 s13, v254, 42
	s_waitcnt lgkmcnt(0)
	v_mov_b32_e32 v0, s2
	v_mov_b32_e32 v4, s3
	ds_read_b32 v3, v0
	ds_read_b32 v2, v4
	v_mov_b32_e32 v5, 0
	v_mov_b32_e32 v6, 1
	s_nop 1
	global_atomic_add v6, v5, v6, s[12:13] sc0
	v_readlane_b32 s2, v254, 45
	v_readlane_b32 s3, v254, 46
	v_readlane_b32 s12, v254, 43
	v_readlane_b32 s13, v254, 44
	s_waitcnt vmcnt(0) lgkmcnt(0)
	v_cvt_f32_u32_e32 v0, v3
	v_sub_u32_e32 v4, 0, v3
	v_rcp_iflag_f32_e32 v0, v0
	s_nop 0
	v_mul_f32_e32 v0, 0x4f7ffffe, v0
	v_cvt_u32_f32_e32 v0, v0
	v_mul_lo_u32 v4, v4, v0
	v_mul_hi_u32 v4, v0, v4
	v_add_u32_e32 v0, v0, v4
	v_mul_hi_u32 v0, v6, v0
	v_mul_lo_u32 v4, v0, v3
	v_sub_u32_e32 v4, v6, v4
	v_add_u32_e32 v7, 1, v0
	v_cmp_ge_u32_e32 vcc, v4, v3
	s_nop 1
	v_cndmask_b32_e32 v0, v0, v7, vcc
	v_sub_u32_e32 v7, v4, v3
	v_cndmask_b32_e32 v4, v4, v7, vcc
	v_add_u32_e32 v7, 1, v0
	v_cmp_ge_u32_e32 vcc, v4, v3
	s_nop 1
	v_cndmask_b32_e32 v0, v0, v7, vcc
	v_add_u32_e32 v7, 1, v0
	v_mul_lo_u32 v4, v7, v3
	v_mul_lo_u32 v7, v7, v2
	v_add_u32_e32 v6, 1, v6
	v_cmp_ne_u32_e32 vcc, v6, v4
	s_mov_b32 s98, 0
	s_cbranch_vccnz .Lxb0_poll
	buffer_wbl2 sc1
	s_waitcnt vmcnt(0)
	v_mov_b32_e32 v6, 1
	global_atomic_add v6, v5, v6, s[2:3] sc0
	v_mov_b32_e32 v4, 1
	s_waitcnt vmcnt(0)
	v_add_u32_e32 v6, 1, v6
	v_cmp_ne_u32_e32 vcc, v6, v7
	s_cbranch_vccnz .Lxb0_poll
	global_atomic_add v5, v4, s[2:3] offset:-4096
	global_atomic_add v5, v4, s[2:3] offset:-3840
	global_atomic_add v5, v4, s[2:3] offset:-3584
	global_atomic_add v5, v4, s[2:3] offset:-3328
	global_atomic_add v5, v4, s[2:3] offset:-3072
	global_atomic_add v5, v4, s[2:3] offset:-2816
	global_atomic_add v5, v4, s[2:3] offset:-2560
	global_atomic_add v5, v4, s[2:3] offset:-2304
	global_atomic_add v5, v4, s[2:3] offset:-2048
	global_atomic_add v5, v4, s[2:3] offset:-1792
	global_atomic_add v5, v4, s[2:3] offset:-1536
	global_atomic_add v5, v4, s[2:3] offset:-1280
	global_atomic_add v5, v4, s[2:3] offset:-1024
	global_atomic_add v5, v4, s[2:3] offset:-768
	global_atomic_add v5, v4, s[2:3] offset:-512
	global_atomic_add v5, v4, s[2:3] offset:-256
	s_branch .Lxb0_done
.Lxb0_poll:
	global_load_dword v6, v5, s[12:13] sc1
	s_waitcnt vmcnt(0)
	v_cmp_eq_u32_e32 vcc, v6, v0
	s_cbranch_vccz .Lxb0_done
	s_sleep 1
	s_add_i32 s98, s98, 1
	s_cmp_lt_u32 s98, 0x40000
	s_cbranch_scc1 .Lxb0_poll

; __device__ __forceinline__ unsigned xb_ld(unsigned* p)              { return __hip_atomic_load(p, __ATOMIC_RELAXED, __HIP_MEMORY_SCOPE_AGENT); }
; __device__ __forceinline__ unsigned xb_add(unsigned* p, unsigned v) { return __hip_atomic_fetch_add(p, v, __ATOMIC_RELAXED, __HIP_MEMORY_SCOPE_AGENT); }
; #define XB_SPIN(cond, bar) do { unsigned _sp = 0; while (cond) { __builtin_amdgcn_s_sleep(1); \
;     if ((++_sp & 255u) == 0u) { if (xb_ld(&(bar)[XB_TMO])) break; if (_sp > XB_SPIN_CAP) { atomicAdd(&(bar)[XB_TMO], 1u); break; } } } } while (0)
; __device__ __forceinline__ void xcd_barrier(const XcdBarrier& b) {
;     ...
;     if (threadIdx.x == 0) {
;         unsigned* bar = b.bar;
;         __builtin_amdgcn_s_waitcnt(0);
;         unsigned nloc = b.st[0], nx = b.st[1];
;         if (nloc == 0u) { xcd_barrier_complete(bar, b.x, nloc, nx); b.st[0] = nloc; b.st[1] = nx; }
;         const unsigned old = xb_add(&bar[XB_XSUB(b.x)], 1u);
;         const unsigned gen = old / nloc;
;         if (old + 1u == (gen + 1u) * nloc) {
;             __builtin_amdgcn_fence(__ATOMIC_RELEASE, "agent");
;             asm volatile("s_waitcnt vmcnt(0)" ::: "memory");
;             const unsigned og = xb_add(&bar[XB_TOP], 1u);
;             const unsigned tg = og / nx;
;             if (og + 1u == (tg + 1u) * nx) xb_add(&bar[XB_TOPGEN], 1u);
;             else XB_SPIN(xb_ld(&bar[XB_TOPGEN]) == tg, bar);
;             __builtin_amdgcn_fence(__ATOMIC_ACQUIRE, "agent");
;             xb_add(&bar[XB_XGEN(b.x)], 1u);
;             asm volatile("s_waitcnt vmcnt(0)" ::: "memory");
;         } else {
;             XB_SPIN(xb_ld(&bar[XB_XGEN(b.x)]) == gen, bar);
;             __builtin_amdgcn_fence(__ATOMIC_ACQUIRE, "agent");
;             asm volatile("s_waitcnt vmcnt(0)" ::: "memory");
;         }
.LBB0_469:
	v_readlane_b32 s2, v254, 59
	v_readlane_b32 s3, v254, 60
	v_readlane_b32 s12, v254, 41
	v_readlane_b32 s13, v254, 42
	s_waitcnt lgkmcnt(0)
	v_mov_b32_e32 v0, s2
	v_mov_b32_e32 v4, s3
	ds_read_b32 v3, v0
	ds_read_b32 v2, v4
	v_mov_b32_e32 v5, 0
	v_mov_b32_e32 v6, 1
	s_nop 1
	global_atomic_add v6, v5, v6, s[12:13] sc0
	v_readlane_b32 s2, v254, 45
	v_readlane_b32 s3, v254, 46
	v_readlane_b32 s12, v254, 43
	v_readlane_b32 s13, v254, 44
	s_waitcnt vmcnt(0) lgkmcnt(0)
	v_cvt_f32_u32_e32 v0, v3
	v_sub_u32_e32 v4, 0, v3
	v_rcp_iflag_f32_e32 v0, v0
	s_nop 0
	v_mul_f32_e32 v0, 0x4f7ffffe, v0
	v_cvt_u32_f32_e32 v0, v0
	v_mul_lo_u32 v4, v4, v0
	v_mul_hi_u32 v4, v0, v4
	v_add_u32_e32 v0, v0, v4
	v_mul_hi_u32 v0, v6, v0
	v_mul_lo_u32 v4, v0, v3
	v_sub_u32_e32 v4, v6, v4
	v_add_u32_e32 v7, 1, v0
	v_cmp_ge_u32_e32 vcc, v4, v3
	s_nop 1
	v_cndmask_b32_e32 v0, v0, v7, vcc
	v_sub_u32_e32 v7, v4, v3
	v_cndmask_b32_e32 v4, v4, v7, vcc
	v_add_u32_e32 v7, 1, v0
	v_cmp_ge_u32_e32 vcc, v4, v3
	s_nop 1
	v_cndmask_b32_e32 v0, v0, v7, vcc
	v_add_u32_e32 v7, 1, v0
	v_mul_lo_u32 v4, v7, v3
	v_mul_lo_u32 v7, v7, v2
	v_add_u32_e32 v6, 1, v6
	v_cmp_ne_u32_e32 vcc, v6, v4
	s_mov_b32 s98, 0
	s_cbranch_vccnz .Lxb1_poll
	buffer_wbl2 sc1
	s_waitcnt vmcnt(0)
	v_mov_b32_e32 v6, 1
	global_atomic_add v6, v5, v6, s[2:3] sc0
	v_mov_b32_e32 v4, 1
	s_waitcnt vmcnt(0)
	v_add_u32_e32 v6, 1, v6
	v_cmp_ne_u32_e32 vcc, v6, v7
	s_cbranch_vccnz .Lxb1_poll
	global_atomic_add v5, v4, s[2:3] offset:-4096
	global_atomic_add v5, v4, s[2:3] offset:-3840
	global_atomic_add v5, v4, s[2:3] offset:-3584
	global_atomic_add v5, v4, s[2:3] offset:-3328
	global_atomic_add v5, v4, s[2:3] offset:-3072
	global_atomic_add v5, v4, s[2:3] offset:-2816
	global_atomic_add v5, v4, s[2:3] offset:-2560
	global_atomic_add v5, v4, s[2:3] offset:-2304
	global_atomic_add v5, v4, s[2:3] offset:-2048
	global_atomic_add v5, v4, s[2:3] offset:-1792
	global_atomic_add v5, v4, s[2:3] offset:-1536
	global_atomic_add v5, v4, s[2:3] offset:-1280
	global_atomic_add v5, v4, s[2:3] offset:-1024
	global_atomic_add v5, v4, s[2:3] offset:-768
	global_atomic_add v5, v4, s[2:3] offset:-512
	global_atomic_add v5, v4, s[2:3] offset:-256
	s_branch .Lxb1_done
